# attention loop: 4-byte encodings for the row-sum adds and clamps, copy adds folded away, second group of K-fragment waits merged
# baseline (speedup 1.0000x reference)
.Latt_sk4:
	s_or_b64 exec, exec, s[44:45]
	v_add_u32_e32 v128, s5, v14
	v_add_u32_e32 v188, s5, v15
	v_min_u32_e32 v128, v245, v128
	v_add_u32_e32 v190, 1, v188
	v_min_u32_e32 v188, v245, v188
	v_min_u32_e32 v190, v245, v190
	v_lshl_add_u32 v130, v128, 12, v238
	v_lshl_add_u32 v132, v128, 6, v239
	v_lshl_add_u32 v188, v188, 12, v174
	v_lshl_add_u32 v190, v190, 12, v174
	global_load_dwordx4 v[128:131], v130, s[98:99]
	s_nop 0
	global_load_dwordx4 v[132:135], v132, s[100:101]
	global_load_dwordx2 v[188:189], v188, s[98:99] offset:128
	global_load_dwordx2 v[190:191], v190, s[98:99] offset:128
	s_branch .LBB0_462
.Latt_sk3:
	s_or_b64 exec, exec, s[46:47]
	v_add_u32_e32 v120, s5, v14
	v_add_u32_e32 v184, s5, v15
	v_min_u32_e32 v120, v245, v120
	v_add_u32_e32 v186, 1, v184
	v_min_u32_e32 v184, v245, v184
	v_min_u32_e32 v186, v245, v186
	v_lshl_add_u32 v122, v120, 12, v238
	v_lshl_add_u32 v124, v120, 6, v239
	v_lshl_add_u32 v184, v184, 12, v174
	v_lshl_add_u32 v186, v186, 12, v174
	global_load_dwordx4 v[120:123], v122, s[98:99]
	s_nop 0
	global_load_dwordx4 v[124:127], v124, s[100:101]
	global_load_dwordx2 v[184:185], v184, s[98:99] offset:128
	global_load_dwordx2 v[186:187], v186, s[98:99] offset:128
	s_branch .LBB0_451
.Latt_sk2:
	s_or_b64 exec, exec, s[44:45]
	v_min_u32_e32 v120, v245, v120
	v_add_u32_e32 v186, 1, v184
	v_min_u32_e32 v184, v245, v184
	v_min_u32_e32 v186, v245, v186
	v_lshl_add_u32 v122, v120, 12, v238
	v_lshl_add_u32 v124, v120, 6, v239
	v_lshl_add_u32 v184, v184, 12, v174
	v_lshl_add_u32 v186, v186, 12, v174
	global_load_dwordx4 v[120:123], v122, s[98:99]
	s_nop 0
	global_load_dwordx4 v[124:127], v124, s[100:101]
	global_load_dwordx2 v[184:185], v184, s[98:99] offset:128
	global_load_dwordx2 v[186:187], v186, s[98:99] offset:128
	s_branch .LBB0_437
.Latt_sk1:
	s_or_b64 exec, exec, s[46:47]
	s_waitcnt vmcnt(3)
	v_add_u32_e32 v2, s5, v221
	v_add_u32_e32 v14, s5, v222
	v_min_u32_e32 v2, v245, v2
	v_add_u32_e32 v192, 1, v14
	v_min_u32_e32 v14, v245, v14
	v_min_u32_e32 v192, v245, v192
	v_lshl_add_u32 v4, v2, 12, v238
	s_waitcnt vmcnt(2)
	v_lshl_add_u32 v6, v2, 6, v239
	v_lshl_add_u32 v14, v14, 12, v174
	v_lshl_add_u32 v192, v192, 12, v174
	global_load_dwordx4 v[2:5], v4, s[98:99]
	s_nop 0
	global_load_dwordx4 v[6:9], v6, s[100:101]
	global_load_dwordx2 v[14:15], v14, s[98:99] offset:128
	global_load_dwordx2 v[192:193], v192, s[98:99] offset:128
	s_branch .LBB0_426

; #define LAS __attribute__((address_space(3)))
; __device__ __forceinline__ void qk_tile(f32x16& s0, f32x16& s1, LAS unsigned char* kb, const bf16x8 (&qr)[6], const f32x16& negm, int r32, int hi) {
;     bf16x8 kf[12];
; #pragma unroll
;     for (int ks = 0; ks < 6; ++ks) { kf[2 * ks] = *(const LAS bf16x8*)(kb + r32 * KPT + ks * 32 + hi * 16); kf[2 * ks + 1] = *(const LAS bf16x8*)(kb + (32 + r32) * KPT + ks * 32 + hi * 16); }
;     __builtin_amdgcn_sched_barrier(0);
; #pragma unroll
;     for (int ks = 0; ks < 6; ++ks) {
;         s0 = __builtin_amdgcn_mfma_f32_32x32x16_bf16(kf[2 * ks], qr[ks], ks == 0 ? negm : s0, 0, 0, 0);
;         s1 = __builtin_amdgcn_mfma_f32_32x32x16_bf16(kf[2 * ks + 1], qr[ks], ks == 0 ? negm : s1, 0, 0, 0);
;     }
.LBB0_418:
	s_add_i32 s85, s84, -3
	s_cmp_lt_u32 s85, s57
	s_cselect_b64 s[44:45], -1, 0
	s_and_b64 s[4:5], s[44:45], exec
	s_cselect_b32 s4, 0, s79
	s_lshl_b32 s4, s4, 6
	v_add_u32_e32 v221, s83, v213
	v_add_u32_e32 v222, s83, v173
	s_sub_i32 s5, 0x80, s4
	v_cmp_le_u32_e32 vcc, s83, v220
	s_and_saveexec_b64 s[46:47], vcc
	s_cbranch_execz .Latt_sk1
	ds_read_b128 v[10:13], v240 offset:13312
	ds_read_b128 v[136:139], v240 offset:13344
	ds_read_b128 v[140:143], v240 offset:19968
	ds_read_b128 v[144:147], v240 offset:20000
	ds_read_b128 v[148:151], v240 offset:13376
	ds_read_b128 v[152:155], v240 offset:13408
	ds_read_b128 v[156:159], v240 offset:20032
	ds_read_b128 v[160:163], v240 offset:20064
	ds_read_b128 v[224:227], v240 offset:13440
	ds_read_b128 v[228:231], v240 offset:13472
	ds_read_b128 v[232:235], v240 offset:20096
	ds_read_b128 v[246:249], v240 offset:20128
	s_waitcnt lgkmcnt(11)
	v_mfma_f32_32x32x16_bf16 v[80:95], v[10:13], v[96:99], v[48:63]
	s_add_i32 s4, s83, 63
	v_cmp_gt_i32_e32 vcc, s4, v175
	s_waitcnt lgkmcnt(9)
	v_mfma_f32_32x32x16_bf16 v[64:79], v[140:143], v[96:99], v[48:63]
	v_mfma_f32_32x32x16_bf16 v[80:95], v[136:139], v[100:103], v[80:95]
	s_waitcnt lgkmcnt(8)
	v_mfma_f32_32x32x16_bf16 v[64:79], v[144:147], v[100:103], v[64:79]
	s_waitcnt lgkmcnt(7)
	v_mfma_f32_32x32x16_bf16 v[80:95], v[148:151], v[104:107], v[80:95]
	s_waitcnt lgkmcnt(5)
	v_mfma_f32_32x32x16_bf16 v[64:79], v[156:159], v[104:107], v[64:79]
	v_mfma_f32_32x32x16_bf16 v[80:95], v[152:155], v[108:111], v[80:95]
	ds_read2_b64 v[152:155], v250 offset0:68 offset1:70
	s_waitcnt lgkmcnt(5)
	v_mfma_f32_32x32x16_bf16 v[64:79], v[160:163], v[108:111], v[64:79]
	ds_read2_b64 v[160:163], v250 offset0:64 offset1:66
	ds_read2_b64 v[156:159], v251 offset0:96 offset1:98
	ds_read2_b64 v[148:151], v251 offset0:100 offset1:102
	ds_read2_b64 v[144:147], v250 offset0:72 offset1:74
	ds_read2_b64 v[140:143], v251 offset0:104 offset1:106
	ds_read2_b64 v[136:139], v250 offset0:76 offset1:78
	ds_read2_b64 v[10:13], v251 offset0:108 offset1:110
	s_waitcnt lgkmcnt(8)
	v_mfma_f32_32x32x16_bf16 v[80:95], v[224:227], v[112:115], v[80:95]
	v_mfma_f32_32x32x16_bf16 v[64:79], v[232:235], v[112:115], v[64:79]
	v_mfma_f32_32x32x16_bf16 v[80:95], v[228:231], v[116:119], v[80:95]
	v_mfma_f32_32x32x16_bf16 v[64:79], v[246:249], v[116:119], v[64:79]
	s_waitcnt vmcnt(3)
	v_add_u32_e32 v2, s5, v221
	v_add_u32_e32 v14, s5, v222
	v_min_u32_e32 v2, v245, v2
	v_add_u32_e32 v192, 1, v14
	v_min_u32_e32 v14, v245, v14
	v_min_u32_e32 v192, v245, v192
	v_lshl_add_u32 v4, v2, 12, v238
	s_waitcnt vmcnt(2)
	v_lshl_add_u32 v6, v2, 6, v239
	v_lshl_add_u32 v14, v14, 12, v174
	v_lshl_add_u32 v192, v192, 12, v174
	global_load_dwordx4 v[2:5], v4, s[98:99]
	s_nop 0
	global_load_dwordx4 v[6:9], v6, s[100:101]
	global_load_dwordx2 v[14:15], v14, s[98:99] offset:128
	global_load_dwordx2 v[192:193], v192, s[98:99] offset:128
	s_and_saveexec_b64 s[58:59], vcc
	s_cbranch_execz .LBB0_423
	v_add_u32_e32 v223, s83, v201
	v_add_u32_e32 v224, 32, v223
	v_cmp_ge_i32_e64 s[4:5], v177, v224
	v_add_u32_e32 v224, 33, v223
	v_cmp_ge_i32_e64 s[6:7], v177, v224
	v_add_u32_e32 v224, 2, v223
	v_cmp_le_u32_e32 vcc, v223, v219
	s_nop 2
	v_cndmask_b32_e64 v65, v244, v65, s[6:7]
	v_cmp_ge_i32_e64 s[6:7], v177, v224
	v_add_u32_e32 v224, 34, v223
	v_cmp_ge_i32_e64 s[8:9], v177, v224
	v_add_u32_e32 v224, 3, v223
	v_cndmask_b32_e64 v64, v244, v64, s[4:5]
	v_cndmask_b32_e64 v66, v244, v66, s[8:9]
	v_cmp_ge_i32_e64 s[8:9], v177, v224
	v_add_u32_e32 v224, 35, v223
	v_cmp_ge_i32_e64 s[10:11], v177, v224
	v_add_u32_e32 v224, 8, v223
	v_cmp_gt_i32_e64 s[4:5], v177, v223
	v_cndmask_b32_e64 v67, v244, v67, s[10:11]
	v_cmp_ge_i32_e64 s[10:11], v177, v224
	v_add_u32_e32 v224, 40, v223
	v_cmp_ge_i32_e64 s[12:13], v177, v224
	v_add_u32_e32 v224, 9, v223
	s_nop 0
	v_cndmask_b32_e64 v68, v244, v68, s[12:13]
	v_cmp_ge_i32_e64 s[12:13], v177, v224
	v_add_u32_e32 v224, 41, v223
	v_cmp_ge_i32_e64 s[14:15], v177, v224
	v_add_u32_e32 v224, 10, v223
	s_nop 0
	v_cndmask_b32_e64 v69, v244, v69, s[14:15]
	v_cmp_ge_i32_e64 s[14:15], v177, v224
	v_add_u32_e32 v224, 42, v223
	v_cmp_ge_i32_e64 s[16:17], v177, v224
	v_add_u32_e32 v224, 11, v223
	s_nop 0
	v_cndmask_b32_e64 v70, v244, v70, s[16:17]
	v_cmp_ge_i32_e64 s[16:17], v177, v224
	v_add_u32_e32 v224, 43, v223
	v_cmp_ge_i32_e64 s[18:19], v177, v224
	v_add_u32_e32 v224, 16, v223
	s_nop 0
	v_cndmask_b32_e64 v71, v244, v71, s[18:19]
	v_cmp_ge_i32_e64 s[18:19], v177, v224
	v_add_u32_e32 v224, 48, v223
	v_cmp_ge_i32_e64 s[20:21], v177, v224
	v_add_u32_e32 v224, 17, v223
	s_nop 0
	v_cndmask_b32_e64 v72, v244, v72, s[20:21]
	v_cmp_ge_i32_e64 s[20:21], v177, v224
	v_add_u32_e32 v224, 49, v223
	v_cmp_ge_i32_e64 s[22:23], v177, v224
	v_add_u32_e32 v224, 18, v223
	s_nop 0
	v_cndmask_b32_e64 v73, v244, v73, s[22:23]
	v_cmp_ge_i32_e64 s[22:23], v177, v224
	v_add_u32_e32 v224, 50, v223
	v_cmp_ge_i32_e64 s[24:25], v177, v224
	v_add_u32_e32 v224, 19, v223
	s_nop 0
	v_cndmask_b32_e64 v74, v244, v74, s[24:25]
	v_cmp_ge_i32_e64 s[24:25], v177, v224
	v_add_u32_e32 v224, 51, v223
	v_cmp_ge_i32_e64 s[26:27], v177, v224
	v_add_u32_e32 v224, 24, v223
	s_nop 0
	v_cndmask_b32_e64 v75, v244, v75, s[26:27]
	v_cmp_ge_i32_e64 s[26:27], v177, v224
	v_add_u32_e32 v224, 56, v223
	v_cmp_ge_i32_e64 s[28:29], v177, v224
	v_add_u32_e32 v224, 25, v223
	s_nop 0
	v_cndmask_b32_e64 v76, v244, v76, s[28:29]
	v_cmp_ge_i32_e64 s[28:29], v177, v224
	v_add_u32_e32 v224, 57, v223
	v_cmp_ge_i32_e64 s[30:31], v177, v224
	v_add_u32_e32 v224, 26, v223
	s_nop 0
	v_cndmask_b32_e64 v77, v244, v77, s[30:31]
	v_cmp_ge_i32_e64 s[30:31], v177, v224
	v_add_u32_e32 v224, 58, v223
	v_cmp_ge_i32_e64 s[34:35], v177, v224
	v_add_u32_e32 v224, 27, v223
	v_add_u32_e32 v223, 59, v223
	v_cndmask_b32_e64 v78, v244, v78, s[34:35]
	v_cmp_ge_i32_e64 s[34:35], v177, v224
	v_cmp_lt_i32_e64 s[36:37], v177, v223
	s_and_saveexec_b64 s[40:41], s[36:37]
	v_mov_b32_e32 v79, s52
	s_or_b64 exec, exec, s[40:41]
	v_cndmask_b32_e32 v80, v244, v80, vcc
	v_cndmask_b32_e64 v81, v244, v81, s[4:5]
	v_cndmask_b32_e64 v82, v244, v82, s[6:7]
	v_cndmask_b32_e64 v83, v244, v83, s[8:9]
	v_cndmask_b32_e64 v84, v244, v84, s[10:11]
	v_cndmask_b32_e64 v85, v244, v85, s[12:13]
	v_cndmask_b32_e64 v86, v244, v86, s[14:15]
	v_cndmask_b32_e64 v87, v244, v87, s[16:17]
	v_cndmask_b32_e64 v88, v244, v88, s[18:19]
	v_cndmask_b32_e64 v89, v244, v89, s[20:21]
	v_cndmask_b32_e64 v90, v244, v90, s[22:23]
	v_cndmask_b32_e64 v91, v244, v91, s[24:25]
	v_cndmask_b32_e64 v92, v244, v92, s[26:27]
	v_cndmask_b32_e64 v93, v244, v93, s[28:29]
	v_cndmask_b32_e64 v94, v244, v94, s[30:31]
	v_cndmask_b32_e64 v95, v244, v95, s[34:35]

; __device__ __forceinline__ unsigned cvtpk(float lo, float hi) { const f32x2 v = {lo, hi}; const bf16x2_t b = __builtin_convertvector(v, bf16x2_t); return __builtin_bit_cast(unsigned, b); }
; __device__ __forceinline__ void sm_pv(f32x16& s0, f32x16& s1, f32x16& o0, f32x16& o1, float& m_run, float& l_run, f32x16& negm, LAS unsigned char* vb, bool domask, int kbase, int qm, int r32, int hi) {
;     ...
;     f32x2 ps2 = (f32x2){0.f, 0.f};
; #pragma unroll
;     for (int r = 0; r < 16; r += 2) { s0[r] = __builtin_amdgcn_exp2f(s0[r]); s0[r + 1] = __builtin_amdgcn_exp2f(s0[r + 1]); s1[r] = __builtin_amdgcn_exp2f(s1[r]); s1[r + 1] = __builtin_amdgcn_exp2f(s1[r + 1]);
;         ps2 += (f32x2){s0[r], s0[r + 1]}; ps2 += (f32x2){s1[r], s1[r + 1]}; }
;     l_run += ps2[0] + ps2[1];
;     u32x4 pw[4];
; #pragma unroll
;     for (int i = 0; i < 4; ++i) { pw[0][i] = cvtpk(s0[2 * i], s0[2 * i + 1]); pw[1][i] = cvtpk(s0[8 + 2 * i], s0[8 + 2 * i + 1]); pw[2][i] = cvtpk(s1[2 * i], s1[2 * i + 1]); pw[3][i] = cvtpk(s1[8 + 2 * i], s1[8 + 2 * i + 1]); }
; #pragma unroll
;     for (int kk = 0; kk < 4; ++kk) {
;         const bf16x8 pf = __builtin_bit_cast(bf16x8, pw[kk]);
;         { const s16x4 lo = vlo[2 * kk], hh = vhh[2 * kk];
;           const bf16x8 vf = (bf16x8){lo[0], lo[1], lo[2], lo[3], hh[0], hh[1], hh[2], hh[3]};
;           o0 = __builtin_amdgcn_mfma_f32_32x32x16_bf16(vf, pf, o0, 0, 0, 0); }
;         { const s16x4 lo = vlo[2 * kk + 1], hh = vhh[2 * kk + 1];
;           const bf16x8 vf = (bf16x8){lo[0], lo[1], lo[2], lo[3], hh[0], hh[1], hh[2], hh[3]};
;           o1 = __builtin_amdgcn_mfma_f32_32x32x16_bf16(vf, pf, o1, 0, 0, 0); }
;     }
.LBB0_425:
	v_exp_f32_e32 v80, v80
	v_exp_f32_e32 v81, v81
	v_exp_f32_e32 v228, v82
	v_exp_f32_e32 v229, v83
	v_exp_f32_e32 v84, v84
	v_exp_f32_e32 v85, v85
	v_exp_f32_e32 v86, v86
	v_exp_f32_e32 v87, v87
	v_exp_f32_e32 v224, v64
	v_exp_f32_e32 v225, v65
	v_add_f32_e32 v226, v224, v80
	v_add_f32_e32 v227, v225, v81
	v_cvt_pk_bf16_f32 v80, v80, v81
	v_cvt_pk_bf16_f32 v81, v228, v229
	v_cvt_pk_bf16_f32 v82, v84, v85
	v_cvt_pk_bf16_f32 v83, v86, v87
	v_exp_f32_e32 v88, v88
	v_exp_f32_e32 v89, v89
	s_waitcnt lgkmcnt(0)
	v_mfma_f32_32x32x16_bf16 v[32:47], v[160:163], v[80:83], v[32:47]
	v_exp_f32_e32 v90, v90
	v_exp_f32_e32 v91, v91
	v_exp_f32_e32 v92, v92
	v_exp_f32_e32 v93, v93
	v_exp_f32_e32 v230, v66
	v_exp_f32_e32 v231, v67
	v_mfma_f32_32x32x16_bf16 v[16:31], v[156:159], v[80:83], v[16:31]
	v_exp_f32_e32 v80, v94
	v_exp_f32_e32 v81, v95
	v_cvt_pk_bf16_f32 v64, v88, v89
	v_cvt_pk_bf16_f32 v65, v90, v91
	v_cvt_pk_bf16_f32 v66, v92, v93
	v_cvt_pk_bf16_f32 v67, v80, v81
	v_exp_f32_e32 v68, v68
	v_exp_f32_e32 v69, v69
	v_mfma_f32_32x32x16_bf16 v[32:47], v[152:155], v[64:67], v[32:47]
	v_exp_f32_e32 v70, v70
	v_exp_f32_e32 v71, v71
	v_add_f32_e32 v82, v228, v226
	v_add_f32_e32 v83, v229, v227
	v_exp_f32_e32 v72, v72
	v_add_f32_e32 v82, v230, v82
	v_add_f32_e32 v83, v231, v83
	v_exp_f32_e32 v73, v73
	v_add_f32_e32 v82, v84, v82
	v_add_f32_e32 v83, v85, v83
	v_mfma_f32_32x32x16_bf16 v[16:31], v[148:151], v[64:67], v[16:31]
	v_cvt_pk_bf16_f32 v64, v224, v225
	v_cvt_pk_bf16_f32 v65, v230, v231
	v_cvt_pk_bf16_f32 v66, v68, v69
	v_cvt_pk_bf16_f32 v67, v70, v71
	v_add_f32_e32 v82, v68, v82
	v_add_f32_e32 v83, v69, v83
	v_add_f32_e32 v82, v86, v82
	v_add_f32_e32 v83, v87, v83
	v_mfma_f32_32x32x16_bf16 v[32:47], v[144:147], v[64:67], v[32:47]
	v_add_f32_e32 v68, v70, v82
	v_add_f32_e32 v69, v71, v83
	v_exp_f32_e32 v70, v74
	v_exp_f32_e32 v71, v75
	v_exp_f32_e32 v74, v76
	v_exp_f32_e32 v75, v77
	v_exp_f32_e32 v76, v78
	v_exp_f32_e32 v77, v79
	v_mfma_f32_32x32x16_bf16 v[16:31], v[140:143], v[64:67], v[16:31]
	v_add_f32_e32 v68, v88, v68
	v_add_f32_e32 v69, v89, v69
	v_cvt_pk_bf16_f32 v64, v72, v73
	v_add_f32_e32 v68, v72, v68
	v_add_f32_e32 v69, v73, v69
	v_cvt_pk_bf16_f32 v65, v70, v71
	v_cvt_pk_bf16_f32 v66, v74, v75
	v_cvt_pk_bf16_f32 v67, v76, v77
	v_add_f32_e32 v68, v90, v68
	v_add_f32_e32 v69, v91, v69
	v_mfma_f32_32x32x16_bf16 v[32:47], v[136:139], v[64:67], v[32:47]
	v_add_f32_e32 v68, v70, v68
	v_add_f32_e32 v69, v71, v69
	v_add_f32_e32 v68, v92, v68
	v_add_f32_e32 v69, v93, v69
	v_add_f32_e32 v68, v74, v68
	v_add_f32_e32 v69, v75, v69
	v_add_f32_e32 v68, v80, v68
	v_add_f32_e32 v69, v81, v69
	v_mfma_f32_32x32x16_bf16 v[16:31], v[10:13], v[64:67], v[16:31]
	v_add_f32_e32 v68, v76, v68
	v_add_f32_e32 v69, v77, v69
	v_add_f32_e32 v68, v68, v69
	v_add_f32_e32 v218, v218, v68
.LBB0_426:
	s_or_b64 exec, exec, s[46:47]
	ds_write_b128 v210, v[120:123]
	s_and_saveexec_b64 s[4:5], s[2:3]
	ds_write_b128 v210, v[124:127] offset:128
	s_or_b64 exec, exec, s[4:5]
	s_waitcnt vmcnt(4)
	v_perm_b32 v10, v186, v184, s94
	v_perm_b32 v11, v186, v184, s95
	ds_write2_b32 v214, v10, v11 offset1:34
	v_perm_b32 v10, v187, v185, s94
	v_perm_b32 v11, v187, v185, s95
	ds_write2_b32 v214, v10, v11 offset0:68 offset1:102
	s_waitcnt lgkmcnt(0)
	s_barrier
	s_andn2_b64 vcc, exec, s[44:45]
	s_cbranch_vccnz .LBB0_417
	s_cmp_gt_u32 s84, s57
	s_cselect_b32 s4, s79, 0
	s_lshl_b32 s4, s4, 6
	s_sub_i32 s5, 0xc0, s4
	v_add_u32_e32 v120, s5, v221
	v_add_u32_e32 v184, s5, v222
	s_add_i32 s4, s83, 64
	v_cmp_le_u32_e32 vcc, s4, v220
	s_and_saveexec_b64 s[44:45], vcc
	s_cbranch_execz .Latt_sk2
	ds_read_b128 v[10:13], v241
	ds_read_b128 v[136:139], v241 offset:32
	ds_read_b128 v[140:143], v241 offset:6656
	ds_read_b128 v[144:147], v241 offset:6688
	ds_read_b128 v[148:151], v241 offset:64
	ds_read_b128 v[152:155], v241 offset:96
	ds_read_b128 v[156:159], v241 offset:6720
	ds_read_b128 v[160:163], v241 offset:6752
	ds_read_b128 v[222:225], v241 offset:128
	ds_read_b128 v[226:229], v241 offset:160
	ds_read_b128 v[230:233], v241 offset:6784
	ds_read_b128 v[234:237], v241 offset:6816
	s_waitcnt lgkmcnt(11)
	v_mfma_f32_32x32x16_bf16 v[80:95], v[10:13], v[96:99], v[48:63]
	s_add_i32 s4, s83, 0x7f
	v_cmp_gt_i32_e32 vcc, s4, v175
	s_waitcnt lgkmcnt(9)
	v_mfma_f32_32x32x16_bf16 v[64:79], v[140:143], v[96:99], v[48:63]
	v_mfma_f32_32x32x16_bf16 v[80:95], v[136:139], v[100:103], v[80:95]
	s_waitcnt lgkmcnt(8)
	v_mfma_f32_32x32x16_bf16 v[64:79], v[144:147], v[100:103], v[64:79]
	s_waitcnt lgkmcnt(7)
	v_mfma_f32_32x32x16_bf16 v[80:95], v[148:151], v[104:107], v[80:95]
	s_waitcnt lgkmcnt(5)
	v_mfma_f32_32x32x16_bf16 v[64:79], v[156:159], v[104:107], v[64:79]
	v_mfma_f32_32x32x16_bf16 v[80:95], v[152:155], v[108:111], v[80:95]
	ds_read2_b64 v[152:155], v252 offset0:4 offset1:6
	s_waitcnt lgkmcnt(5)
	v_mfma_f32_32x32x16_bf16 v[64:79], v[160:163], v[108:111], v[64:79]
	ds_read2_b64 v[160:163], v252 offset1:2
	ds_read2_b64 v[156:159], v253 offset0:32 offset1:34
	ds_read2_b64 v[148:151], v253 offset0:36 offset1:38
	ds_read2_b64 v[144:147], v252 offset0:8 offset1:10
	ds_read2_b64 v[140:143], v253 offset0:40 offset1:42
	ds_read2_b64 v[136:139], v252 offset0:12 offset1:14
	ds_read2_b64 v[10:13], v253 offset0:44 offset1:46
	s_waitcnt lgkmcnt(8)
	v_mfma_f32_32x32x16_bf16 v[80:95], v[222:225], v[112:115], v[80:95]
	v_mfma_f32_32x32x16_bf16 v[64:79], v[230:233], v[112:115], v[64:79]
	v_mfma_f32_32x32x16_bf16 v[80:95], v[226:229], v[116:119], v[80:95]
	v_mfma_f32_32x32x16_bf16 v[64:79], v[234:237], v[116:119], v[64:79]
	v_min_u32_e32 v120, v245, v120
	v_add_u32_e32 v186, 1, v184
	v_min_u32_e32 v184, v245, v184
	v_min_u32_e32 v186, v245, v186
	v_lshl_add_u32 v122, v120, 12, v238
	v_lshl_add_u32 v124, v120, 6, v239
	v_lshl_add_u32 v184, v184, 12, v174
	v_lshl_add_u32 v186, v186, 12, v174
	global_load_dwordx4 v[120:123], v122, s[98:99]
	s_nop 0
	global_load_dwordx4 v[124:127], v124, s[100:101]
	global_load_dwordx2 v[184:185], v184, s[98:99] offset:128
	global_load_dwordx2 v[186:187], v186, s[98:99] offset:128
	s_and_saveexec_b64 s[46:47], vcc
	s_cbranch_execz .LBB0_434
; __device__ __forceinline__ void sm_pv(f32x16& s0, f32x16& s1, f32x16& o0, f32x16& o1, float& m_run, float& l_run, f32x16& negm, LAS unsigned char* vb, bool domask, int kbase, int qm, int r32, int hi) {
;     ...
;     if (domask) {
;         const int kb0 = kbase + 4 * hi;
; #pragma unroll
;         for (int r = 0; r < 16; ++r) { const int kv = kb0 + (r & 3) + 8 * (r >> 2); if (kv > qm) s0[r] = -INFINITY; if (kv + 32 > qm) s1[r] = -INFINITY; }
;     }
	v_add_u32_e32 v221, s83, v201
	v_add_u32_e32 v223, 0x60, v221
	v_add_u32_e32 v222, 64, v221
	v_cmp_le_u32_e64 s[4:5], v223, v219
	v_cmp_le_u32_e32 vcc, v222, v219
	s_nop 4
	v_cndmask_b32_e64 v64, v244, v64, s[4:5]
	v_cmp_lt_u32_e64 s[4:5], v222, v219
	v_add_u32_e32 v222, 0x61, v221
	v_cmp_le_u32_e64 s[6:7], v222, v219
	v_add_u32_e32 v222, 0x42, v221
	s_nop 0
	v_cndmask_b32_e64 v65, v244, v65, s[6:7]
	v_cmp_le_u32_e64 s[6:7], v222, v219
	v_add_u32_e32 v222, 0x62, v221
	v_cmp_le_u32_e64 s[8:9], v222, v219
	v_add_u32_e32 v222, 0x43, v221
	s_nop 0
	v_cndmask_b32_e64 v66, v244, v66, s[8:9]
	v_cmp_le_u32_e64 s[8:9], v222, v219
	v_add_u32_e32 v222, 0x63, v221
	v_cmp_le_u32_e64 s[10:11], v222, v219
	v_add_u32_e32 v222, 0x48, v221
	s_nop 0
	v_cndmask_b32_e64 v67, v244, v67, s[10:11]
	v_cmp_le_u32_e64 s[10:11], v222, v219
	v_add_u32_e32 v222, 0x68, v221
	v_cmp_le_u32_e64 s[12:13], v222, v219
	v_add_u32_e32 v222, 0x49, v221
	s_nop 0
	v_cndmask_b32_e64 v68, v244, v68, s[12:13]
	v_cmp_le_u32_e64 s[12:13], v222, v219
	v_add_u32_e32 v222, 0x69, v221
	v_cmp_le_u32_e64 s[14:15], v222, v219
	v_add_u32_e32 v222, 0x4a, v221
	s_nop 0
	v_cndmask_b32_e64 v69, v244, v69, s[14:15]
	v_cmp_le_u32_e64 s[14:15], v222, v219
	v_add_u32_e32 v222, 0x6a, v221
	v_cmp_le_u32_e64 s[16:17], v222, v219
	v_add_u32_e32 v222, 0x4b, v221
	s_nop 0
	v_cndmask_b32_e64 v70, v244, v70, s[16:17]
	v_cmp_le_u32_e64 s[16:17], v222, v219
	v_add_u32_e32 v222, 0x6b, v221
	v_cmp_le_u32_e64 s[18:19], v222, v219
	v_add_u32_e32 v222, 0x50, v221
	s_nop 0
	v_cndmask_b32_e64 v71, v244, v71, s[18:19]
	v_cmp_le_u32_e64 s[18:19], v222, v219
	v_add_u32_e32 v222, 0x70, v221
	v_cmp_le_u32_e64 s[20:21], v222, v219
	v_add_u32_e32 v222, 0x51, v221
	s_nop 0
	v_cndmask_b32_e64 v72, v244, v72, s[20:21]
	v_cmp_le_u32_e64 s[20:21], v222, v219
	v_add_u32_e32 v222, 0x71, v221
	v_cmp_le_u32_e64 s[22:23], v222, v219
	v_add_u32_e32 v222, 0x52, v221
	s_nop 0
	v_cndmask_b32_e64 v73, v244, v73, s[22:23]
	v_cmp_le_u32_e64 s[22:23], v222, v219
	v_add_u32_e32 v222, 0x72, v221
	v_cmp_le_u32_e64 s[24:25], v222, v219
	v_add_u32_e32 v222, 0x53, v221
	s_nop 0
	v_cndmask_b32_e64 v74, v244, v74, s[24:25]
	v_cmp_le_u32_e64 s[24:25], v222, v219
	v_add_u32_e32 v222, 0x73, v221
	v_cmp_le_u32_e64 s[26:27], v222, v219
	v_add_u32_e32 v222, 0x58, v221
	s_nop 0
	v_cndmask_b32_e64 v75, v244, v75, s[26:27]
	v_cmp_le_u32_e64 s[26:27], v222, v219
	v_add_u32_e32 v222, 0x78, v221
	v_cmp_le_u32_e64 s[28:29], v222, v219
	v_add_u32_e32 v222, 0x59, v221
	s_nop 0
	v_cndmask_b32_e64 v76, v244, v76, s[28:29]
	v_cmp_le_u32_e64 s[28:29], v222, v219
	v_add_u32_e32 v222, 0x79, v221
	v_cmp_le_u32_e64 s[30:31], v222, v219
	v_add_u32_e32 v222, 0x5a, v221
	s_nop 0
	v_cndmask_b32_e64 v77, v244, v77, s[30:31]
	v_cmp_le_u32_e64 s[30:31], v222, v219
	v_add_u32_e32 v222, 0x7a, v221
	v_cmp_le_u32_e64 s[34:35], v222, v219
	v_add_u32_e32 v222, 0x5b, v221
	v_add_u32_e32 v221, 0x7b, v221
	v_cndmask_b32_e64 v78, v244, v78, s[34:35]
	v_cmp_le_u32_e64 s[34:35], v222, v219
	v_cmp_gt_u32_e64 s[36:37], v221, v219
	s_and_saveexec_b64 s[40:41], s[36:37]
	v_mov_b32_e32 v79, s52
	s_or_b64 exec, exec, s[40:41]
	v_cndmask_b32_e64 v81, v244, v81, s[4:5]
	v_cndmask_b32_e32 v80, v244, v80, vcc
	v_cndmask_b32_e64 v82, v244, v82, s[6:7]
	v_cndmask_b32_e64 v83, v244, v83, s[8:9]
	v_cndmask_b32_e64 v84, v244, v84, s[10:11]
	v_cndmask_b32_e64 v85, v244, v85, s[12:13]
	v_cndmask_b32_e64 v86, v244, v86, s[14:15]
	v_cndmask_b32_e64 v87, v244, v87, s[16:17]
	v_cndmask_b32_e64 v88, v244, v88, s[18:19]
	v_cndmask_b32_e64 v89, v244, v89, s[20:21]
	v_cndmask_b32_e64 v90, v244, v90, s[22:23]
	v_cndmask_b32_e64 v91, v244, v91, s[24:25]
	v_cndmask_b32_e64 v92, v244, v92, s[26:27]
	v_cndmask_b32_e64 v93, v244, v93, s[28:29]
	v_cndmask_b32_e64 v94, v244, v94, s[30:31]
	v_cndmask_b32_e64 v95, v244, v95, s[34:35]

; __device__ __forceinline__ unsigned cvtpk(float lo, float hi) { const f32x2 v = {lo, hi}; const bf16x2_t b = __builtin_convertvector(v, bf16x2_t); return __builtin_bit_cast(unsigned, b); }
; __device__ __forceinline__ void sm_pv(f32x16& s0, f32x16& s1, f32x16& o0, f32x16& o1, float& m_run, float& l_run, f32x16& negm, LAS unsigned char* vb, bool domask, int kbase, int qm, int r32, int hi) {
;     ...
;     f32x2 ps2 = (f32x2){0.f, 0.f};
; #pragma unroll
;     for (int r = 0; r < 16; r += 2) { s0[r] = __builtin_amdgcn_exp2f(s0[r]); s0[r + 1] = __builtin_amdgcn_exp2f(s0[r + 1]); s1[r] = __builtin_amdgcn_exp2f(s1[r]); s1[r + 1] = __builtin_amdgcn_exp2f(s1[r + 1]);
;         ps2 += (f32x2){s0[r], s0[r + 1]}; ps2 += (f32x2){s1[r], s1[r + 1]}; }
;     l_run += ps2[0] + ps2[1];
;     u32x4 pw[4];
; #pragma unroll
;     for (int i = 0; i < 4; ++i) { pw[0][i] = cvtpk(s0[2 * i], s0[2 * i + 1]); pw[1][i] = cvtpk(s0[8 + 2 * i], s0[8 + 2 * i + 1]); pw[2][i] = cvtpk(s1[2 * i], s1[2 * i + 1]); pw[3][i] = cvtpk(s1[8 + 2 * i], s1[8 + 2 * i + 1]); }
; #pragma unroll
;     for (int kk = 0; kk < 4; ++kk) {
;         const bf16x8 pf = __builtin_bit_cast(bf16x8, pw[kk]);
;         { const s16x4 lo = vlo[2 * kk], hh = vhh[2 * kk];
;           const bf16x8 vf = (bf16x8){lo[0], lo[1], lo[2], lo[3], hh[0], hh[1], hh[2], hh[3]};
;           o0 = __builtin_amdgcn_mfma_f32_32x32x16_bf16(vf, pf, o0, 0, 0, 0); }
;         { const s16x4 lo = vlo[2 * kk + 1], hh = vhh[2 * kk + 1];
;           const bf16x8 vf = (bf16x8){lo[0], lo[1], lo[2], lo[3], hh[0], hh[1], hh[2], hh[3]};
;           o1 = __builtin_amdgcn_mfma_f32_32x32x16_bf16(vf, pf, o1, 0, 0, 0); }
;     }
.LBB0_436:
	v_exp_f32_e32 v80, v80
	v_exp_f32_e32 v81, v81
	v_exp_f32_e32 v226, v82
	v_exp_f32_e32 v227, v83
	v_exp_f32_e32 v84, v84
	v_exp_f32_e32 v85, v85
	v_exp_f32_e32 v86, v86
	v_exp_f32_e32 v87, v87
	v_exp_f32_e32 v222, v64
	v_exp_f32_e32 v223, v65
	v_add_f32_e32 v224, v222, v80
	v_add_f32_e32 v225, v223, v81
	v_cvt_pk_bf16_f32 v80, v80, v81
	v_cvt_pk_bf16_f32 v81, v226, v227
	v_cvt_pk_bf16_f32 v82, v84, v85
	v_cvt_pk_bf16_f32 v83, v86, v87
	v_exp_f32_e32 v88, v88
	v_exp_f32_e32 v89, v89
	s_waitcnt lgkmcnt(0)
	v_mfma_f32_32x32x16_bf16 v[32:47], v[160:163], v[80:83], v[32:47]
	v_exp_f32_e32 v90, v90
	v_exp_f32_e32 v91, v91
	v_exp_f32_e32 v92, v92
	v_exp_f32_e32 v93, v93
	v_exp_f32_e32 v228, v66
	v_exp_f32_e32 v229, v67
	v_mfma_f32_32x32x16_bf16 v[16:31], v[156:159], v[80:83], v[16:31]
	v_exp_f32_e32 v80, v94
	v_exp_f32_e32 v81, v95
	v_cvt_pk_bf16_f32 v64, v88, v89
	v_cvt_pk_bf16_f32 v65, v90, v91
	v_cvt_pk_bf16_f32 v66, v92, v93
	v_cvt_pk_bf16_f32 v67, v80, v81
	v_exp_f32_e32 v68, v68
	v_exp_f32_e32 v69, v69
	v_mfma_f32_32x32x16_bf16 v[32:47], v[152:155], v[64:67], v[32:47]
	v_exp_f32_e32 v70, v70
	v_exp_f32_e32 v71, v71
	v_add_f32_e32 v82, v226, v224
	v_add_f32_e32 v83, v227, v225
	v_exp_f32_e32 v72, v72
	v_add_f32_e32 v82, v228, v82
	v_add_f32_e32 v83, v229, v83
	v_exp_f32_e32 v73, v73
	v_add_f32_e32 v82, v84, v82
	v_add_f32_e32 v83, v85, v83
	v_mfma_f32_32x32x16_bf16 v[16:31], v[148:151], v[64:67], v[16:31]
	v_cvt_pk_bf16_f32 v64, v222, v223
	v_cvt_pk_bf16_f32 v65, v228, v229
	v_cvt_pk_bf16_f32 v66, v68, v69
	v_cvt_pk_bf16_f32 v67, v70, v71
	v_add_f32_e32 v82, v68, v82
	v_add_f32_e32 v83, v69, v83
	v_add_f32_e32 v82, v86, v82
	v_add_f32_e32 v83, v87, v83
	v_mfma_f32_32x32x16_bf16 v[32:47], v[144:147], v[64:67], v[32:47]
	v_add_f32_e32 v68, v70, v82
	v_add_f32_e32 v69, v71, v83
	v_exp_f32_e32 v70, v74
	v_exp_f32_e32 v71, v75
	v_exp_f32_e32 v74, v76
	v_exp_f32_e32 v75, v77
	v_exp_f32_e32 v76, v78
	v_exp_f32_e32 v77, v79
	v_mfma_f32_32x32x16_bf16 v[16:31], v[140:143], v[64:67], v[16:31]
	v_add_f32_e32 v68, v88, v68
	v_add_f32_e32 v69, v89, v69
	v_cvt_pk_bf16_f32 v64, v72, v73
	v_add_f32_e32 v68, v72, v68
	v_add_f32_e32 v69, v73, v69
	v_cvt_pk_bf16_f32 v65, v70, v71
	v_cvt_pk_bf16_f32 v66, v74, v75
	v_cvt_pk_bf16_f32 v67, v76, v77
	v_add_f32_e32 v68, v90, v68
	v_add_f32_e32 v69, v91, v69
	v_mfma_f32_32x32x16_bf16 v[32:47], v[136:139], v[64:67], v[32:47]
	v_add_f32_e32 v68, v70, v68
	v_add_f32_e32 v69, v71, v69
	v_add_f32_e32 v68, v92, v68
	v_add_f32_e32 v69, v93, v69
	v_add_f32_e32 v68, v74, v68
	v_add_f32_e32 v69, v75, v69
	v_add_f32_e32 v68, v80, v68
	v_add_f32_e32 v69, v81, v69
	v_mfma_f32_32x32x16_bf16 v[16:31], v[10:13], v[64:67], v[16:31]
	v_add_f32_e32 v68, v76, v68
	v_add_f32_e32 v69, v77, v69
	v_add_f32_e32 v68, v68, v69
	v_add_f32_e32 v218, v218, v68

; #define LAS __attribute__((address_space(3)))
; __device__ __forceinline__ void qk_tile(f32x16& s0, f32x16& s1, LAS unsigned char* kb, const bf16x8 (&qr)[6], const f32x16& negm, int r32, int hi) {
;     bf16x8 kf[12];
; #pragma unroll
;     for (int ks = 0; ks < 6; ++ks) { kf[2 * ks] = *(const LAS bf16x8*)(kb + r32 * KPT + ks * 32 + hi * 16); kf[2 * ks + 1] = *(const LAS bf16x8*)(kb + (32 + r32) * KPT + ks * 32 + hi * 16); }
;     __builtin_amdgcn_sched_barrier(0);
; #pragma unroll
;     for (int ks = 0; ks < 6; ++ks) {
;         s0 = __builtin_amdgcn_mfma_f32_32x32x16_bf16(kf[2 * ks], qr[ks], ks == 0 ? negm : s0, 0, 0, 0);
;         s1 = __builtin_amdgcn_mfma_f32_32x32x16_bf16(kf[2 * ks + 1], qr[ks], ks == 0 ? negm : s1, 0, 0, 0);
;     }
; }
; __device__ __forceinline__ void sm_pv(f32x16& s0, f32x16& s1, f32x16& o0, f32x16& o1, float& m_run, float& l_run, f32x16& negm, LAS unsigned char* vb, bool domask, int kbase, int qm, int r32, int hi) {
;     s16x4 vlo[8], vhh[8];
; #pragma unroll
;     for (int kk = 0; kk < 4; ++kk) { const int koff = 2 * (16 * kk + 4 * hi);
;         vlo[2 * kk] = *(const LAS s16x4*)(vb + r32 * VP + koff); vhh[2 * kk] = *(const LAS s16x4*)(vb + r32 * VP + koff + 16);
;         vlo[2 * kk + 1] = *(const LAS s16x4*)(vb + (32 + r32) * VP + koff); vhh[2 * kk + 1] = *(const LAS s16x4*)(vb + (32 + r32) * VP + koff + 16); }
;     __builtin_amdgcn_sched_barrier(0);
;     if (domask) {
;         const int kb0 = kbase + 4 * hi;
; #pragma unroll
;         for (int r = 0; r < 16; ++r) { const int kv = kb0 + (r & 3) + 8 * (r >> 2); if (kv > qm) s0[r] = -INFINITY; if (kv + 32 > qm) s1[r] = -INFINITY; }
;     }
.LBB0_443:
	s_add_i32 s85, s84, -3
	s_cmp_lt_u32 s85, s57
	s_cselect_b64 s[44:45], -1, 0
	s_and_b64 s[4:5], s[44:45], exec
	s_cselect_b32 s4, 0, s79
	s_lshl_b32 s4, s4, 6
	s_sub_i32 s5, 0x80, s4
	v_add_u32_e32 v14, s83, v213
	v_add_u32_e32 v15, s83, v173
	v_cmp_le_u32_e32 vcc, s83, v220
	s_and_saveexec_b64 s[46:47], vcc
	s_cbranch_execz .Latt_sk3
	ds_read_b128 v[2:5], v241
	ds_read_b128 v[6:9], v241 offset:32
	ds_read_b128 v[10:13], v241 offset:6656
	ds_read_b128 v[136:139], v241 offset:6688
	ds_read_b128 v[140:143], v241 offset:64
	ds_read_b128 v[144:147], v241 offset:96
	ds_read_b128 v[148:151], v241 offset:6720
	ds_read_b128 v[152:155], v241 offset:6752
	ds_read_b128 v[156:159], v241 offset:128
	ds_read_b128 v[160:163], v241 offset:160
	ds_read_b128 v[222:225], v241 offset:6784
	ds_read_b128 v[226:229], v241 offset:6816
	s_waitcnt lgkmcnt(11)
	v_mfma_f32_32x32x16_bf16 v[80:95], v[2:5], v[96:99], v[48:63]
	s_add_i32 s4, s83, 63
	v_cmp_gt_i32_e32 vcc, s4, v175
	s_waitcnt lgkmcnt(9)
	v_mfma_f32_32x32x16_bf16 v[64:79], v[10:13], v[96:99], v[48:63]
	v_mfma_f32_32x32x16_bf16 v[80:95], v[6:9], v[100:103], v[80:95]
	s_waitcnt lgkmcnt(8)
	v_mfma_f32_32x32x16_bf16 v[64:79], v[136:139], v[100:103], v[64:79]
	s_waitcnt lgkmcnt(7)
	v_mfma_f32_32x32x16_bf16 v[80:95], v[140:143], v[104:107], v[80:95]
	s_waitcnt lgkmcnt(5)
	v_mfma_f32_32x32x16_bf16 v[64:79], v[148:151], v[104:107], v[64:79]
	v_mfma_f32_32x32x16_bf16 v[80:95], v[144:147], v[108:111], v[80:95]
	ds_read2_b64 v[144:147], v252 offset0:4 offset1:6
	s_waitcnt lgkmcnt(5)
	v_mfma_f32_32x32x16_bf16 v[64:79], v[152:155], v[108:111], v[64:79]
	ds_read2_b64 v[152:155], v252 offset1:2
	ds_read2_b64 v[148:151], v253 offset0:32 offset1:34
	ds_read2_b64 v[140:143], v253 offset0:36 offset1:38
	ds_read2_b64 v[136:139], v252 offset0:8 offset1:10
	ds_read2_b64 v[10:13], v253 offset0:40 offset1:42
	ds_read2_b64 v[6:9], v252 offset0:12 offset1:14
	ds_read2_b64 v[2:5], v253 offset0:44 offset1:46
	s_waitcnt lgkmcnt(8)
	v_mfma_f32_32x32x16_bf16 v[80:95], v[156:159], v[112:115], v[80:95]
	v_mfma_f32_32x32x16_bf16 v[64:79], v[222:225], v[112:115], v[64:79]
	v_mfma_f32_32x32x16_bf16 v[80:95], v[160:163], v[116:119], v[80:95]
	v_mfma_f32_32x32x16_bf16 v[64:79], v[226:229], v[116:119], v[64:79]
	v_add_u32_e32 v120, s5, v14
	v_add_u32_e32 v184, s5, v15
	v_min_u32_e32 v120, v245, v120
	v_add_u32_e32 v186, 1, v184
	v_min_u32_e32 v184, v245, v184
	v_min_u32_e32 v186, v245, v186
	v_lshl_add_u32 v122, v120, 12, v238
	v_lshl_add_u32 v124, v120, 6, v239
	v_lshl_add_u32 v184, v184, 12, v174
	v_lshl_add_u32 v186, v186, 12, v174
	global_load_dwordx4 v[120:123], v122, s[98:99]
	s_nop 0
	global_load_dwordx4 v[124:127], v124, s[100:101]
	global_load_dwordx2 v[184:185], v184, s[98:99] offset:128
	global_load_dwordx2 v[186:187], v186, s[98:99] offset:128
	s_and_saveexec_b64 s[58:59], vcc
	s_cbranch_execz .LBB0_448
	v_add_u32_e32 v156, s83, v201
	v_add_u32_e32 v157, 32, v156
	v_cmp_ge_i32_e64 s[4:5], v177, v157
	v_add_u32_e32 v157, 33, v156
	v_cmp_ge_i32_e64 s[6:7], v177, v157
	v_add_u32_e32 v157, 2, v156
	v_cmp_le_u32_e32 vcc, v156, v219
	s_nop 2
	v_cndmask_b32_e64 v65, v244, v65, s[6:7]
	v_cmp_ge_i32_e64 s[6:7], v177, v157
	v_add_u32_e32 v157, 34, v156
	v_cmp_ge_i32_e64 s[8:9], v177, v157
	v_add_u32_e32 v157, 3, v156
	v_cndmask_b32_e64 v64, v244, v64, s[4:5]
	v_cndmask_b32_e64 v66, v244, v66, s[8:9]
	v_cmp_ge_i32_e64 s[8:9], v177, v157
	v_add_u32_e32 v157, 35, v156
	v_cmp_ge_i32_e64 s[10:11], v177, v157
	v_add_u32_e32 v157, 8, v156
	v_cmp_gt_i32_e64 s[4:5], v177, v156
	v_cndmask_b32_e64 v67, v244, v67, s[10:11]
	v_cmp_ge_i32_e64 s[10:11], v177, v157
	v_add_u32_e32 v157, 40, v156
	v_cmp_ge_i32_e64 s[12:13], v177, v157
	v_add_u32_e32 v157, 9, v156
	s_nop 0
	v_cndmask_b32_e64 v68, v244, v68, s[12:13]
	v_cmp_ge_i32_e64 s[12:13], v177, v157
	v_add_u32_e32 v157, 41, v156
	v_cmp_ge_i32_e64 s[14:15], v177, v157
	v_add_u32_e32 v157, 10, v156
	s_nop 0
	v_cndmask_b32_e64 v69, v244, v69, s[14:15]
	v_cmp_ge_i32_e64 s[14:15], v177, v157
	v_add_u32_e32 v157, 42, v156
	v_cmp_ge_i32_e64 s[16:17], v177, v157
	v_add_u32_e32 v157, 11, v156
	s_nop 0
	v_cndmask_b32_e64 v70, v244, v70, s[16:17]
	v_cmp_ge_i32_e64 s[16:17], v177, v157
	v_add_u32_e32 v157, 43, v156
	v_cmp_ge_i32_e64 s[18:19], v177, v157
	v_add_u32_e32 v157, 16, v156
	s_nop 0
	v_cndmask_b32_e64 v71, v244, v71, s[18:19]
	v_cmp_ge_i32_e64 s[18:19], v177, v157
	v_add_u32_e32 v157, 48, v156
	v_cmp_ge_i32_e64 s[20:21], v177, v157
	v_add_u32_e32 v157, 17, v156
	s_nop 0
	v_cndmask_b32_e64 v72, v244, v72, s[20:21]
	v_cmp_ge_i32_e64 s[20:21], v177, v157
	v_add_u32_e32 v157, 49, v156
	v_cmp_ge_i32_e64 s[22:23], v177, v157
	v_add_u32_e32 v157, 18, v156
	s_nop 0
	v_cndmask_b32_e64 v73, v244, v73, s[22:23]
	v_cmp_ge_i32_e64 s[22:23], v177, v157
	v_add_u32_e32 v157, 50, v156
	v_cmp_ge_i32_e64 s[24:25], v177, v157
	v_add_u32_e32 v157, 19, v156
	s_nop 0
	v_cndmask_b32_e64 v74, v244, v74, s[24:25]
	v_cmp_ge_i32_e64 s[24:25], v177, v157
	v_add_u32_e32 v157, 51, v156
	v_cmp_ge_i32_e64 s[26:27], v177, v157
	v_add_u32_e32 v157, 24, v156
	s_nop 0
	v_cndmask_b32_e64 v75, v244, v75, s[26:27]
	v_cmp_ge_i32_e64 s[26:27], v177, v157
	v_add_u32_e32 v157, 56, v156
	v_cmp_ge_i32_e64 s[28:29], v177, v157
	v_add_u32_e32 v157, 25, v156
	s_nop 0
	v_cndmask_b32_e64 v76, v244, v76, s[28:29]
	v_cmp_ge_i32_e64 s[28:29], v177, v157
	v_add_u32_e32 v157, 57, v156
	v_cmp_ge_i32_e64 s[30:31], v177, v157
	v_add_u32_e32 v157, 26, v156
	s_nop 0
	v_cndmask_b32_e64 v77, v244, v77, s[30:31]
	v_cmp_ge_i32_e64 s[30:31], v177, v157
	v_add_u32_e32 v157, 58, v156
	v_cmp_ge_i32_e64 s[34:35], v177, v157
	v_add_u32_e32 v157, 27, v156
	v_add_u32_e32 v156, 59, v156
	v_cndmask_b32_e64 v78, v244, v78, s[34:35]
	v_cmp_ge_i32_e64 s[34:35], v177, v157
	v_cmp_lt_i32_e64 s[36:37], v177, v156
	s_and_saveexec_b64 s[40:41], s[36:37]
	v_mov_b32_e32 v79, s52
	s_or_b64 exec, exec, s[40:41]
	v_cndmask_b32_e32 v80, v244, v80, vcc
	v_cndmask_b32_e64 v81, v244, v81, s[4:5]
	v_cndmask_b32_e64 v82, v244, v82, s[6:7]
	v_cndmask_b32_e64 v83, v244, v83, s[8:9]
	v_cndmask_b32_e64 v84, v244, v84, s[10:11]
	v_cndmask_b32_e64 v85, v244, v85, s[12:13]
	v_cndmask_b32_e64 v86, v244, v86, s[14:15]
	v_cndmask_b32_e64 v87, v244, v87, s[16:17]
	v_cndmask_b32_e64 v88, v244, v88, s[18:19]
	v_cndmask_b32_e64 v89, v244, v89, s[20:21]
	v_cndmask_b32_e64 v90, v244, v90, s[22:23]
	v_cndmask_b32_e64 v91, v244, v91, s[24:25]
	v_cndmask_b32_e64 v92, v244, v92, s[26:27]
	v_cndmask_b32_e64 v93, v244, v93, s[28:29]
	v_cndmask_b32_e64 v94, v244, v94, s[30:31]
	v_cndmask_b32_e64 v95, v244, v95, s[34:35]

; __device__ __forceinline__ unsigned cvtpk(float lo, float hi) { const f32x2 v = {lo, hi}; const bf16x2_t b = __builtin_convertvector(v, bf16x2_t); return __builtin_bit_cast(unsigned, b); }
; __device__ __forceinline__ void sm_pv(f32x16& s0, f32x16& s1, f32x16& o0, f32x16& o1, float& m_run, float& l_run, f32x16& negm, LAS unsigned char* vb, bool domask, int kbase, int qm, int r32, int hi) {
;     ...
;     f32x2 ps2 = (f32x2){0.f, 0.f};
; #pragma unroll
;     for (int r = 0; r < 16; r += 2) { s0[r] = __builtin_amdgcn_exp2f(s0[r]); s0[r + 1] = __builtin_amdgcn_exp2f(s0[r + 1]); s1[r] = __builtin_amdgcn_exp2f(s1[r]); s1[r + 1] = __builtin_amdgcn_exp2f(s1[r + 1]);
;         ps2 += (f32x2){s0[r], s0[r + 1]}; ps2 += (f32x2){s1[r], s1[r + 1]}; }
;     l_run += ps2[0] + ps2[1];
;     u32x4 pw[4];
; #pragma unroll
;     for (int i = 0; i < 4; ++i) { pw[0][i] = cvtpk(s0[2 * i], s0[2 * i + 1]); pw[1][i] = cvtpk(s0[8 + 2 * i], s0[8 + 2 * i + 1]); pw[2][i] = cvtpk(s1[2 * i], s1[2 * i + 1]); pw[3][i] = cvtpk(s1[8 + 2 * i], s1[8 + 2 * i + 1]); }
; #pragma unroll
;     for (int kk = 0; kk < 4; ++kk) {
;         const bf16x8 pf = __builtin_bit_cast(bf16x8, pw[kk]);
;         { const s16x4 lo = vlo[2 * kk], hh = vhh[2 * kk];
;           const bf16x8 vf = (bf16x8){lo[0], lo[1], lo[2], lo[3], hh[0], hh[1], hh[2], hh[3]};
;           o0 = __builtin_amdgcn_mfma_f32_32x32x16_bf16(vf, pf, o0, 0, 0, 0); }
;         { const s16x4 lo = vlo[2 * kk + 1], hh = vhh[2 * kk + 1];
;           const bf16x8 vf = (bf16x8){lo[0], lo[1], lo[2], lo[3], hh[0], hh[1], hh[2], hh[3]};
;           o1 = __builtin_amdgcn_mfma_f32_32x32x16_bf16(vf, pf, o1, 0, 0, 0); }
;     }
.LBB0_450:
	v_exp_f32_e32 v80, v80
	v_exp_f32_e32 v81, v81
	v_exp_f32_e32 v160, v82
	v_exp_f32_e32 v161, v83
	v_exp_f32_e32 v84, v84
	v_exp_f32_e32 v85, v85
	v_exp_f32_e32 v86, v86
	v_exp_f32_e32 v87, v87
	v_exp_f32_e32 v156, v64
	v_exp_f32_e32 v157, v65
	v_add_f32_e32 v158, v156, v80
	v_add_f32_e32 v159, v157, v81
	v_cvt_pk_bf16_f32 v80, v80, v81
	v_cvt_pk_bf16_f32 v81, v160, v161
	v_cvt_pk_bf16_f32 v82, v84, v85
	v_cvt_pk_bf16_f32 v83, v86, v87
	v_exp_f32_e32 v88, v88
	v_exp_f32_e32 v89, v89
	s_waitcnt lgkmcnt(0)
	v_mfma_f32_32x32x16_bf16 v[32:47], v[152:155], v[80:83], v[32:47]
	v_exp_f32_e32 v90, v90
	v_exp_f32_e32 v91, v91
	v_exp_f32_e32 v92, v92
	v_exp_f32_e32 v93, v93
	v_exp_f32_e32 v162, v66
	v_exp_f32_e32 v163, v67
	v_mfma_f32_32x32x16_bf16 v[16:31], v[148:151], v[80:83], v[16:31]
	v_exp_f32_e32 v80, v94
	v_exp_f32_e32 v81, v95
	v_cvt_pk_bf16_f32 v64, v88, v89
	v_cvt_pk_bf16_f32 v65, v90, v91
	v_cvt_pk_bf16_f32 v66, v92, v93
	v_cvt_pk_bf16_f32 v67, v80, v81
	v_exp_f32_e32 v68, v68
	v_exp_f32_e32 v69, v69
	v_mfma_f32_32x32x16_bf16 v[32:47], v[144:147], v[64:67], v[32:47]
	v_exp_f32_e32 v70, v70
	v_exp_f32_e32 v71, v71
	v_add_f32_e32 v82, v160, v158
	v_add_f32_e32 v83, v161, v159
	v_exp_f32_e32 v72, v72
	v_add_f32_e32 v82, v162, v82
	v_add_f32_e32 v83, v163, v83
	v_exp_f32_e32 v73, v73
	v_add_f32_e32 v82, v84, v82
	v_add_f32_e32 v83, v85, v83
	v_mfma_f32_32x32x16_bf16 v[16:31], v[140:143], v[64:67], v[16:31]
	v_cvt_pk_bf16_f32 v64, v156, v157
	v_cvt_pk_bf16_f32 v65, v162, v163
	v_cvt_pk_bf16_f32 v66, v68, v69
	v_cvt_pk_bf16_f32 v67, v70, v71
	v_add_f32_e32 v82, v68, v82
	v_add_f32_e32 v83, v69, v83
	v_add_f32_e32 v82, v86, v82
	v_add_f32_e32 v83, v87, v83
	v_mfma_f32_32x32x16_bf16 v[32:47], v[136:139], v[64:67], v[32:47]
	v_add_f32_e32 v68, v70, v82
	v_add_f32_e32 v69, v71, v83
	v_exp_f32_e32 v70, v74
	v_exp_f32_e32 v71, v75
	v_exp_f32_e32 v74, v76
	v_exp_f32_e32 v75, v77
	v_add_f32_e32 v68, v88, v68
	v_add_f32_e32 v69, v89, v69
	v_mfma_f32_32x32x16_bf16 v[16:31], v[10:13], v[64:67], v[16:31]
	v_exp_f32_e32 v64, v78
	v_exp_f32_e32 v65, v79
	v_add_f32_e32 v68, v72, v68
	v_add_f32_e32 v69, v73, v69
	v_cvt_pk_bf16_f32 v10, v72, v73
	v_add_f32_e32 v68, v90, v68
	v_add_f32_e32 v69, v91, v69
	v_cvt_pk_bf16_f32 v11, v70, v71
	v_cvt_pk_bf16_f32 v12, v74, v75
	v_cvt_pk_bf16_f32 v13, v64, v65
	s_nop 0
	v_mfma_f32_32x32x16_bf16 v[32:47], v[6:9], v[10:13], v[32:47]
	v_add_f32_e32 v6, v70, v68
	v_add_f32_e32 v7, v71, v69
	v_add_f32_e32 v6, v92, v6
	v_add_f32_e32 v7, v93, v7
	v_add_f32_e32 v6, v74, v6
	v_add_f32_e32 v7, v75, v7
	v_add_f32_e32 v6, v80, v6
	v_add_f32_e32 v7, v81, v7
	v_mfma_f32_32x32x16_bf16 v[16:31], v[2:5], v[10:13], v[16:31]
	v_add_f32_e32 v6, v64, v6
	v_add_f32_e32 v7, v65, v7
	v_add_f32_e32 v6, v6, v7
	v_add_f32_e32 v218, v218, v6

; #define LAS __attribute__((address_space(3)))
; __device__ __forceinline__ void qk_tile(f32x16& s0, f32x16& s1, LAS unsigned char* kb, const bf16x8 (&qr)[6], const f32x16& negm, int r32, int hi) {
;     bf16x8 kf[12];
; #pragma unroll
;     for (int ks = 0; ks < 6; ++ks) { kf[2 * ks] = *(const LAS bf16x8*)(kb + r32 * KPT + ks * 32 + hi * 16); kf[2 * ks + 1] = *(const LAS bf16x8*)(kb + (32 + r32) * KPT + ks * 32 + hi * 16); }
;     __builtin_amdgcn_sched_barrier(0);
; #pragma unroll
;     for (int ks = 0; ks < 6; ++ks) {
;         s0 = __builtin_amdgcn_mfma_f32_32x32x16_bf16(kf[2 * ks], qr[ks], ks == 0 ? negm : s0, 0, 0, 0);
;         s1 = __builtin_amdgcn_mfma_f32_32x32x16_bf16(kf[2 * ks + 1], qr[ks], ks == 0 ? negm : s1, 0, 0, 0);
;     }
; }
; __device__ __forceinline__ void sm_pv(f32x16& s0, f32x16& s1, f32x16& o0, f32x16& o1, float& m_run, float& l_run, f32x16& negm, LAS unsigned char* vb, bool domask, int kbase, int qm, int r32, int hi) {
;     s16x4 vlo[8], vhh[8];
; #pragma unroll
;     for (int kk = 0; kk < 4; ++kk) { const int koff = 2 * (16 * kk + 4 * hi);
;         vlo[2 * kk] = *(const LAS s16x4*)(vb + r32 * VP + koff); vhh[2 * kk] = *(const LAS s16x4*)(vb + r32 * VP + koff + 16);
;         vlo[2 * kk + 1] = *(const LAS s16x4*)(vb + (32 + r32) * VP + koff); vhh[2 * kk + 1] = *(const LAS s16x4*)(vb + (32 + r32) * VP + koff + 16); }
;     __builtin_amdgcn_sched_barrier(0);
;     if (domask) {
;         const int kb0 = kbase + 4 * hi;
; #pragma unroll
;         for (int r = 0; r < 16; ++r) { const int kv = kb0 + (r & 3) + 8 * (r >> 2); if (kv > qm) s0[r] = -INFINITY; if (kv + 32 > qm) s1[r] = -INFINITY; }
;     }
.LBB0_453:
	s_or_b64 exec, exec, s[4:5]
	s_waitcnt vmcnt(4)
	v_perm_b32 v2, v190, v188, s94
	v_perm_b32 v3, v190, v188, s95
	ds_write2_b32 v254, v2, v3 offset0:128 offset1:162
	v_perm_b32 v2, v191, v189, s94
	v_perm_b32 v3, v191, v189, s95
	ds_write2_b32 v254, v2, v3 offset0:196 offset1:230
	s_waitcnt lgkmcnt(0)
	s_barrier
	s_andn2_b64 vcc, exec, s[44:45]
	s_cbranch_vccnz .LBB0_442
	s_cmp_gt_u32 s84, s57
	s_cselect_b32 s4, s79, 0
	s_lshl_b32 s4, s4, 6
	s_sub_i32 s5, 0xc0, s4
	s_add_i32 s4, s83, 64
	v_cmp_le_u32_e32 vcc, s4, v220
	s_and_saveexec_b64 s[44:45], vcc
	s_cbranch_execz .Latt_sk4
	ds_read_b128 v[2:5], v240 offset:13312
	ds_read_b128 v[6:9], v240 offset:13344
	ds_read_b128 v[10:13], v240 offset:19968
	ds_read_b128 v[136:139], v240 offset:20000
	ds_read_b128 v[140:143], v240 offset:13376
	ds_read_b128 v[144:147], v240 offset:13408
	ds_read_b128 v[148:151], v240 offset:20032
	ds_read_b128 v[152:155], v240 offset:20064
	ds_read_b128 v[156:159], v240 offset:13440
	ds_read_b128 v[160:163], v240 offset:13472
	ds_read_b128 v[222:225], v240 offset:20096
	ds_read_b128 v[226:229], v240 offset:20128
	s_waitcnt lgkmcnt(11)
	v_mfma_f32_32x32x16_bf16 v[80:95], v[2:5], v[96:99], v[48:63]
	s_add_i32 s4, s83, 0x7f
	v_cmp_gt_i32_e32 vcc, s4, v175
	s_waitcnt lgkmcnt(9)
	v_mfma_f32_32x32x16_bf16 v[64:79], v[10:13], v[96:99], v[48:63]
	v_mfma_f32_32x32x16_bf16 v[80:95], v[6:9], v[100:103], v[80:95]
	s_waitcnt lgkmcnt(8)
	v_mfma_f32_32x32x16_bf16 v[64:79], v[136:139], v[100:103], v[64:79]
	s_waitcnt lgkmcnt(7)
	v_mfma_f32_32x32x16_bf16 v[80:95], v[140:143], v[104:107], v[80:95]
	s_waitcnt lgkmcnt(5)
	v_mfma_f32_32x32x16_bf16 v[64:79], v[148:151], v[104:107], v[64:79]
	v_mfma_f32_32x32x16_bf16 v[80:95], v[144:147], v[108:111], v[80:95]
	ds_read2_b64 v[144:147], v250 offset0:68 offset1:70
	s_waitcnt lgkmcnt(5)
	v_mfma_f32_32x32x16_bf16 v[64:79], v[152:155], v[108:111], v[64:79]
	ds_read2_b64 v[152:155], v250 offset0:64 offset1:66
	ds_read2_b64 v[148:151], v251 offset0:96 offset1:98
	ds_read2_b64 v[140:143], v251 offset0:100 offset1:102
	ds_read2_b64 v[136:139], v250 offset0:72 offset1:74
	ds_read2_b64 v[10:13], v251 offset0:104 offset1:106
	ds_read2_b64 v[6:9], v250 offset0:76 offset1:78
	ds_read2_b64 v[2:5], v251 offset0:108 offset1:110
	s_waitcnt lgkmcnt(8)
	v_mfma_f32_32x32x16_bf16 v[80:95], v[156:159], v[112:115], v[80:95]
	v_mfma_f32_32x32x16_bf16 v[64:79], v[222:225], v[112:115], v[64:79]
	v_mfma_f32_32x32x16_bf16 v[80:95], v[160:163], v[116:119], v[80:95]
	v_mfma_f32_32x32x16_bf16 v[64:79], v[226:229], v[116:119], v[64:79]
	v_add_u32_e32 v128, s5, v14
	v_add_u32_e32 v188, s5, v15
	v_min_u32_e32 v128, v245, v128
	v_add_u32_e32 v190, 1, v188
	v_min_u32_e32 v188, v245, v188
	v_min_u32_e32 v190, v245, v190
	v_lshl_add_u32 v130, v128, 12, v238
	v_lshl_add_u32 v132, v128, 6, v239
	v_lshl_add_u32 v188, v188, 12, v174
	v_lshl_add_u32 v190, v190, 12, v174
	global_load_dwordx4 v[128:131], v130, s[98:99]
	s_nop 0
	global_load_dwordx4 v[132:135], v132, s[100:101]
	global_load_dwordx2 v[188:189], v188, s[98:99] offset:128
	global_load_dwordx2 v[190:191], v190, s[98:99] offset:128
	s_and_saveexec_b64 s[46:47], vcc
	s_cbranch_execz .LBB0_459
	v_add_u32_e32 v14, s83, v201
	v_add_u32_e32 v156, 0x60, v14
	v_add_u32_e32 v15, 64, v14
	v_cmp_le_u32_e64 s[4:5], v156, v219
	v_cmp_le_u32_e32 vcc, v15, v219
	s_nop 4
	v_cndmask_b32_e64 v64, v244, v64, s[4:5]
	v_cmp_lt_u32_e64 s[4:5], v15, v219
	v_add_u32_e32 v15, 0x61, v14
	v_cmp_le_u32_e64 s[6:7], v15, v219
	v_add_u32_e32 v15, 0x42, v14
	s_nop 0
	v_cndmask_b32_e64 v65, v244, v65, s[6:7]
	v_cmp_le_u32_e64 s[6:7], v15, v219
	v_add_u32_e32 v15, 0x62, v14
	v_cmp_le_u32_e64 s[8:9], v15, v219
	v_add_u32_e32 v15, 0x43, v14
	s_nop 0
	v_cndmask_b32_e64 v66, v244, v66, s[8:9]
	v_cmp_le_u32_e64 s[8:9], v15, v219
	v_add_u32_e32 v15, 0x63, v14
	v_cmp_le_u32_e64 s[10:11], v15, v219
	v_add_u32_e32 v15, 0x48, v14
	s_nop 0
	v_cndmask_b32_e64 v67, v244, v67, s[10:11]
	v_cmp_le_u32_e64 s[10:11], v15, v219
	v_add_u32_e32 v15, 0x68, v14
	v_cmp_le_u32_e64 s[12:13], v15, v219
	v_add_u32_e32 v15, 0x49, v14
	s_nop 0
	v_cndmask_b32_e64 v68, v244, v68, s[12:13]
	v_cmp_le_u32_e64 s[12:13], v15, v219
	v_add_u32_e32 v15, 0x69, v14
	v_cmp_le_u32_e64 s[14:15], v15, v219
	v_add_u32_e32 v15, 0x4a, v14
	s_nop 0
	v_cndmask_b32_e64 v69, v244, v69, s[14:15]
	v_cmp_le_u32_e64 s[14:15], v15, v219
	v_add_u32_e32 v15, 0x6a, v14
	v_cmp_le_u32_e64 s[16:17], v15, v219
	v_add_u32_e32 v15, 0x4b, v14
	s_nop 0
	v_cndmask_b32_e64 v70, v244, v70, s[16:17]
	v_cmp_le_u32_e64 s[16:17], v15, v219
	v_add_u32_e32 v15, 0x6b, v14
	v_cmp_le_u32_e64 s[18:19], v15, v219
	v_add_u32_e32 v15, 0x50, v14
	s_nop 0
	v_cndmask_b32_e64 v71, v244, v71, s[18:19]
	v_cmp_le_u32_e64 s[18:19], v15, v219
	v_add_u32_e32 v15, 0x70, v14
	v_cmp_le_u32_e64 s[20:21], v15, v219
	v_add_u32_e32 v15, 0x51, v14
	s_nop 0
	v_cndmask_b32_e64 v72, v244, v72, s[20:21]
	v_cmp_le_u32_e64 s[20:21], v15, v219
	v_add_u32_e32 v15, 0x71, v14
	v_cmp_le_u32_e64 s[22:23], v15, v219
	v_add_u32_e32 v15, 0x52, v14
	s_nop 0
	v_cndmask_b32_e64 v73, v244, v73, s[22:23]
	v_cmp_le_u32_e64 s[22:23], v15, v219
	v_add_u32_e32 v15, 0x72, v14
	v_cmp_le_u32_e64 s[24:25], v15, v219
	v_add_u32_e32 v15, 0x53, v14
	s_nop 0
	v_cndmask_b32_e64 v74, v244, v74, s[24:25]
	v_cmp_le_u32_e64 s[24:25], v15, v219
	v_add_u32_e32 v15, 0x73, v14
	v_cmp_le_u32_e64 s[26:27], v15, v219
	v_add_u32_e32 v15, 0x58, v14
	s_nop 0
	v_cndmask_b32_e64 v75, v244, v75, s[26:27]
	v_cmp_le_u32_e64 s[26:27], v15, v219
	v_add_u32_e32 v15, 0x78, v14
	v_cmp_le_u32_e64 s[28:29], v15, v219
	v_add_u32_e32 v15, 0x59, v14
	s_nop 0
	v_cndmask_b32_e64 v76, v244, v76, s[28:29]
	v_cmp_le_u32_e64 s[28:29], v15, v219
	v_add_u32_e32 v15, 0x79, v14
	v_cmp_le_u32_e64 s[30:31], v15, v219
	v_add_u32_e32 v15, 0x5a, v14
	s_nop 0
	v_cndmask_b32_e64 v77, v244, v77, s[30:31]
	v_cmp_le_u32_e64 s[30:31], v15, v219
	v_add_u32_e32 v15, 0x7a, v14
	v_cmp_le_u32_e64 s[34:35], v15, v219
	v_add_u32_e32 v15, 0x5b, v14
	v_add_u32_e32 v14, 0x7b, v14
	v_cndmask_b32_e64 v78, v244, v78, s[34:35]
	v_cmp_le_u32_e64 s[34:35], v15, v219
	v_cmp_gt_u32_e64 s[36:37], v14, v219
	s_and_saveexec_b64 s[40:41], s[36:37]
	v_mov_b32_e32 v79, s52
	s_or_b64 exec, exec, s[40:41]
	v_cndmask_b32_e64 v81, v244, v81, s[4:5]
	v_cndmask_b32_e32 v80, v244, v80, vcc
	v_cndmask_b32_e64 v82, v244, v82, s[6:7]
	v_cndmask_b32_e64 v83, v244, v83, s[8:9]
	v_cndmask_b32_e64 v84, v244, v84, s[10:11]
	v_cndmask_b32_e64 v85, v244, v85, s[12:13]
	v_cndmask_b32_e64 v86, v244, v86, s[14:15]
	v_cndmask_b32_e64 v87, v244, v87, s[16:17]
	v_cndmask_b32_e64 v88, v244, v88, s[18:19]
	v_cndmask_b32_e64 v89, v244, v89, s[20:21]
	v_cndmask_b32_e64 v90, v244, v90, s[22:23]
	v_cndmask_b32_e64 v91, v244, v91, s[24:25]
	v_cndmask_b32_e64 v92, v244, v92, s[26:27]
	v_cndmask_b32_e64 v93, v244, v93, s[28:29]
	v_cndmask_b32_e64 v94, v244, v94, s[30:31]
	v_cndmask_b32_e64 v95, v244, v95, s[34:35]

; __device__ __forceinline__ unsigned cvtpk(float lo, float hi) { const f32x2 v = {lo, hi}; const bf16x2_t b = __builtin_convertvector(v, bf16x2_t); return __builtin_bit_cast(unsigned, b); }
; __device__ __forceinline__ void sm_pv(f32x16& s0, f32x16& s1, f32x16& o0, f32x16& o1, float& m_run, float& l_run, f32x16& negm, LAS unsigned char* vb, bool domask, int kbase, int qm, int r32, int hi) {
;     ...
;     f32x2 ps2 = (f32x2){0.f, 0.f};
; #pragma unroll
;     for (int r = 0; r < 16; r += 2) { s0[r] = __builtin_amdgcn_exp2f(s0[r]); s0[r + 1] = __builtin_amdgcn_exp2f(s0[r + 1]); s1[r] = __builtin_amdgcn_exp2f(s1[r]); s1[r + 1] = __builtin_amdgcn_exp2f(s1[r + 1]);
;         ps2 += (f32x2){s0[r], s0[r + 1]}; ps2 += (f32x2){s1[r], s1[r + 1]}; }
;     l_run += ps2[0] + ps2[1];
;     u32x4 pw[4];
; #pragma unroll
;     for (int i = 0; i < 4; ++i) { pw[0][i] = cvtpk(s0[2 * i], s0[2 * i + 1]); pw[1][i] = cvtpk(s0[8 + 2 * i], s0[8 + 2 * i + 1]); pw[2][i] = cvtpk(s1[2 * i], s1[2 * i + 1]); pw[3][i] = cvtpk(s1[8 + 2 * i], s1[8 + 2 * i + 1]); }
; #pragma unroll
;     for (int kk = 0; kk < 4; ++kk) {
;         const bf16x8 pf = __builtin_bit_cast(bf16x8, pw[kk]);
;         { const s16x4 lo = vlo[2 * kk], hh = vhh[2 * kk];
;           const bf16x8 vf = (bf16x8){lo[0], lo[1], lo[2], lo[3], hh[0], hh[1], hh[2], hh[3]};
;           o0 = __builtin_amdgcn_mfma_f32_32x32x16_bf16(vf, pf, o0, 0, 0, 0); }
;         { const s16x4 lo = vlo[2 * kk + 1], hh = vhh[2 * kk + 1];
;           const bf16x8 vf = (bf16x8){lo[0], lo[1], lo[2], lo[3], hh[0], hh[1], hh[2], hh[3]};
;           o1 = __builtin_amdgcn_mfma_f32_32x32x16_bf16(vf, pf, o1, 0, 0, 0); }
;     }
.LBB0_461:
	v_exp_f32_e32 v14, v80
	v_exp_f32_e32 v15, v81
	v_exp_f32_e32 v160, v82
	v_exp_f32_e32 v161, v83
	v_exp_f32_e32 v84, v84
	v_exp_f32_e32 v85, v85
	v_exp_f32_e32 v86, v86
	v_exp_f32_e32 v87, v87
	v_cvt_pk_bf16_f32 v80, v14, v15
	v_cvt_pk_bf16_f32 v81, v160, v161
	v_cvt_pk_bf16_f32 v82, v84, v85
	v_cvt_pk_bf16_f32 v83, v86, v87
	v_exp_f32_e32 v156, v64
	v_exp_f32_e32 v157, v65
	s_waitcnt lgkmcnt(0)
	v_mfma_f32_32x32x16_bf16 v[32:47], v[152:155], v[80:83], v[32:47]
	v_exp_f32_e32 v88, v88
	v_exp_f32_e32 v89, v89
	v_exp_f32_e32 v90, v90
	v_exp_f32_e32 v91, v91
	v_exp_f32_e32 v92, v92
	v_exp_f32_e32 v93, v93
	v_add_f32_e32 v158, v156, v14
	v_add_f32_e32 v159, v157, v15
	v_mfma_f32_32x32x16_bf16 v[16:31], v[148:151], v[80:83], v[16:31]
	v_exp_f32_e32 v80, v94
	v_exp_f32_e32 v81, v95
	v_exp_f32_e32 v162, v66
	v_exp_f32_e32 v163, v67
	v_cvt_pk_bf16_f32 v64, v88, v89
	v_cvt_pk_bf16_f32 v65, v90, v91
	v_cvt_pk_bf16_f32 v66, v92, v93
	v_cvt_pk_bf16_f32 v67, v80, v81
	v_exp_f32_e32 v14, v68
	v_exp_f32_e32 v15, v69
	v_mfma_f32_32x32x16_bf16 v[32:47], v[144:147], v[64:67], v[32:47]
	v_exp_f32_e32 v70, v70
	v_exp_f32_e32 v71, v71
	v_add_f32_e32 v68, v160, v158
	v_add_f32_e32 v69, v161, v159
	v_exp_f32_e32 v72, v72
	v_add_f32_e32 v68, v162, v68
	v_add_f32_e32 v69, v163, v69
	v_exp_f32_e32 v73, v73
	v_add_f32_e32 v68, v84, v68
	v_add_f32_e32 v69, v85, v69
	v_mfma_f32_32x32x16_bf16 v[16:31], v[140:143], v[64:67], v[16:31]
	v_cvt_pk_bf16_f32 v64, v156, v157
	v_cvt_pk_bf16_f32 v65, v162, v163
	v_cvt_pk_bf16_f32 v66, v14, v15
	v_cvt_pk_bf16_f32 v67, v70, v71
	v_add_f32_e32 v68, v14, v68
	v_add_f32_e32 v69, v15, v69
	v_add_f32_e32 v68, v86, v68
	v_add_f32_e32 v69, v87, v69
	v_mfma_f32_32x32x16_bf16 v[32:47], v[136:139], v[64:67], v[32:47]
	v_add_f32_e32 v14, v70, v68
	v_add_f32_e32 v15, v71, v69
	v_exp_f32_e32 v68, v74
	v_exp_f32_e32 v69, v75
	v_exp_f32_e32 v70, v76
	v_exp_f32_e32 v71, v77
	v_add_f32_e32 v14, v88, v14
	v_add_f32_e32 v15, v89, v15
	v_mfma_f32_32x32x16_bf16 v[16:31], v[10:13], v[64:67], v[16:31]
	v_exp_f32_e32 v64, v78
	v_exp_f32_e32 v65, v79
	v_add_f32_e32 v14, v72, v14
	v_add_f32_e32 v15, v73, v15
	v_cvt_pk_bf16_f32 v10, v72, v73
	v_cvt_pk_bf16_f32 v11, v68, v69
	v_cvt_pk_bf16_f32 v12, v70, v71
	v_cvt_pk_bf16_f32 v13, v64, v65
	v_add_f32_e32 v14, v90, v14
	v_add_f32_e32 v15, v91, v15
	v_mfma_f32_32x32x16_bf16 v[32:47], v[6:9], v[10:13], v[32:47]
	v_add_f32_e32 v6, v68, v14
	v_add_f32_e32 v7, v69, v15
	v_add_f32_e32 v6, v92, v6
	v_add_f32_e32 v7, v93, v7
	v_add_f32_e32 v6, v70, v6
	v_add_f32_e32 v7, v71, v7
	v_add_f32_e32 v6, v80, v6
	v_add_f32_e32 v7, v81, v7
	v_mfma_f32_32x32x16_bf16 v[16:31], v[2:5], v[10:13], v[16:31]
	v_add_f32_e32 v6, v64, v6
	v_add_f32_e32 v7, v65, v7
	v_add_f32_e32 v6, v6, v7
	v_add_f32_e32 v218, v218, v6
